# row-stat exchange of fused out-proj epilogue: sign-bit generation tag in the slot value, readers poll the data (no store-ack wait, counter atomic, counter poll; 2 fewer WG barriers per exchange); slot
# baseline (speedup 1.0000x reference)
.LBB0_7:
.LBB0_8:
	v_readlane_b32 s8, v253, 0
	v_readlane_b32 s9, v253, 1
	s_mov_b64 s[16:17], s[8:9]
	s_load_dwordx4 s[4:7], s[16:17], 0x18
	s_load_dwordx2 s[10:11], s[16:17], 0x28
	s_load_dwordx2 s[0:1], s[16:17], 0x98
	v_mov_b32_e32 v2, v216
	s_load_dword s22, s[8:9], 0xb0
	s_add_u32 s8, s8, 0xb0
	s_movk_i32 s12, 0x1400
	v_readfirstlane_b32 s23, v2
	s_addc_u32 s9, s9, 0
	s_waitcnt lgkmcnt(0)
	s_lshl_b32 s100, s2, 11
	s_lshl_b32 s101, s22, 11
	v_lshlrev_b32_e32 v1, 2, v216
	v_add_u32_e32 v1, 0x5800000, v1
	v_bfrev_b32_e32 v3, 1
.Lrsx_init:
	s_cmp_lt_u32 s100, 0x80000
	s_cbranch_scc0 .Lrsx_init_done
	v_add_u32_e32 v4, s100, v1
	global_store_dword v4, v3, s[0:1] sc1
	s_add_u32 s100, s100, s101
	s_branch .Lrsx_init
.Lrsx_init_done:
	v_cmp_gt_i32_e32 vcc, s12, v2
	s_and_saveexec_b64 s[12:13], vcc
	s_cbranch_execz .LBB0_11
	s_load_dwordx2 s[18:19], s[16:17], 0x8
	v_ashrrev_i32_e32 v3, 31, v2
	v_lshl_add_u32 v1, v2, 2, 0
	s_mov_b64 s[16:17], 0
	s_movk_i32 s24, 0x1000
	s_waitcnt lgkmcnt(0)
	v_lshl_add_u64 v[4:5], v[2:3], 2, s[18:19]
	s_movk_i32 s18, 0xc000
	v_mov_b32_e32 v7, 0
	s_mov_b32 s19, -1
	s_mov_b64 s[20:21], 0x800
	s_movk_i32 s25, 0x11ff
	v_mov_b32_e32 v6, v2

.LBB0_1553:
	s_or_b64 exec, exec, s[34:35]
	v_readlane_b32 s100, v254, 16
	s_lshl_b32 s100, s100, 31
	s_ashr_i32 s13, s12, 31
	s_lshl_b64 s[34:35], s[12:13], 12
	s_add_u32 s13, s18, s34
	s_addc_u32 s35, s19, s35
	s_add_u32 s34, s13, 0x5800000
	v_lshlrev_b32_e32 v154, 2, v32
	s_addc_u32 s35, s35, 0
	v_ashrrev_i32_e32 v155, 31, v154
	s_waitcnt vmcnt(0) lgkmcnt(0)
	s_barrier
	s_and_saveexec_b64 s[46:47], s[8:9]
	s_cbranch_execz .LBB0_1555
	v_lshl_add_u32 v153, v32, 4, 0
	ds_read_b128 v[158:161], v153
	v_lshl_add_u64 v[162:163], v[154:155], 2, s[34:35]
	s_ashr_i32 s43, s42, 31
	v_lshl_add_u64 v[162:163], s[42:43], 2, v[162:163]
	s_waitcnt lgkmcnt(0)
	v_mov_b32_e32 v164, v159
	v_mov_b32_e32 v165, v160
	v_mov_b32_e32 v159, v161
	v_pk_add_f32 v[158:159], v[164:165], v[158:159]
	s_nop 0
	v_pk_add_f32 v[158:159], v[158:159], v[158:159] op_sel:[0,1] op_sel_hi:[1,0]
	v_or_b32_e32 v158, s100, v158
	global_store_dword v[162:163], v158, off sc1
.LBB0_1555:
	s_or_b64 exec, exec, s[46:47]
	v_cmp_eq_u32_e32 vcc, 0, v32
	s_and_saveexec_b64 s[12:13], s[8:9]
	s_cbranch_execz .LBB0_1571
	v_lshl_add_u64 v[162:163], v[154:155], 2, s[34:35]
	s_mov_b32 s8, 0x800000
	s_movk_i32 s101, 0x7fff
.Lrsx_poll0:
	global_load_dwordx4 v[158:161], v[162:163], off sc1
	s_waitcnt vmcnt(0)
	v_xor_b32_e32 v158, s100, v158
	v_xor_b32_e32 v159, s100, v159
	v_xor_b32_e32 v160, s100, v160
	v_xor_b32_e32 v161, s100, v161
	v_or3_b32 v153, v158, v159, v160
	v_or_b32_e32 v153, v153, v161
	v_cmp_gt_i32_e32 vcc, 0, v153
	s_cbranch_vccz .Lrsx_ok0
	s_sleep 1
	s_add_i32 s101, s101, -1
	s_cmp_lg_u32 s101, 0
	s_cbranch_scc1 .Lrsx_poll0
.Lrsx_ok0:
	v_add_f32_e32 v153, v158, v159
	v_add_f32_e32 v160, v160, v161
	v_add_f32_e32 v32, v153, v160
	v_fmamk_f32 v32, v32, 0x3a800000, v239
	v_mul_f32_e32 v153, 0x4b800000, v32
	v_cmp_gt_f32_e32 vcc, s8, v32
	s_nop 1
	v_cndmask_b32_e32 v32, v32, v153, vcc
	v_rsq_f32_e32 v32, v32
	s_nop 0
	v_mul_f32_e32 v153, 0x45800000, v32
	v_cndmask_b32_e32 v32, v32, v153, vcc
	v_add_u32_e32 v153, 0, v154
	ds_write_b32 v153, v32 offset:4096

.LBB0_1643:
	s_or_b64 exec, exec, s[12:13]
	v_readlane_b32 s100, v254, 16
	s_lshl_b32 s100, s100, 31
	s_ashr_i32 s17, s16, 31
	s_lshl_b64 s[48:49], s[16:17], 12
	s_add_u32 s12, s18, s48
	s_addc_u32 s13, s19, s49
	s_add_u32 s34, s12, 0x5800000
	v_lshlrev_b32_e32 v34, 2, v32
	s_addc_u32 s35, s13, 0
	v_ashrrev_i32_e32 v35, 31, v34
	v_lshl_add_u32 v175, v32, 4, 0
	s_waitcnt vmcnt(0) lgkmcnt(0)
	s_barrier
	s_and_saveexec_b64 s[12:13], s[8:9]
	s_cbranch_execz .LBB0_1645
	ds_read_b128 v[154:157], v175
	v_lshl_add_u64 v[158:159], v[34:35], 2, s[34:35]
	s_ashr_i32 s43, s42, 31
	v_lshl_add_u64 v[158:159], s[42:43], 2, v[158:159]
	s_waitcnt lgkmcnt(0)
	v_mov_b32_e32 v162, v155
	v_mov_b32_e32 v163, v156
	v_mov_b32_e32 v155, v157
	v_pk_add_f32 v[154:155], v[162:163], v[154:155]
	s_nop 0
	v_pk_add_f32 v[154:155], v[154:155], v[154:155] op_sel:[0,1] op_sel_hi:[1,0]
	v_or_b32_e32 v154, s100, v154
	global_store_dword v[158:159], v154, off sc1
.LBB0_1645:
	s_or_b64 exec, exec, s[12:13]
	s_add_u32 s17, s18, 0x8000
	v_readlane_b32 s12, v254, 16
	s_addc_u32 s70, s19, 0
	s_lshl_b32 s12, s12, 11
	s_lshl_b32 s13, s16, 4
	s_add_i32 s46, s13, s12
	v_cmp_eq_u32_e64 s[12:13], 0, v32
	s_mov_b64 s[52:53], 0x14801000
	v_lshl_add_u64 v[166:167], v[150:151], 0, s[52:53]
	s_mov_b64 s[52:53], 0x14801800
	v_lshl_add_u64 v[164:165], v[150:151], 0, s[52:53]
	v_add_u32_e32 v174, 0, v34
	s_and_saveexec_b64 s[52:53], s[8:9]
	s_cbranch_execz .LBB0_1661
	v_lshl_add_u64 v[158:159], v[34:35], 2, s[34:35]
	s_mov_b32 s34, 0x800000
	s_movk_i32 s101, 0x7fff
.Lrsx_poll1:
	global_load_dwordx4 v[154:157], v[158:159], off sc1
	s_waitcnt vmcnt(0)
	v_xor_b32_e32 v154, s100, v154
	v_xor_b32_e32 v155, s100, v155
	v_xor_b32_e32 v156, s100, v156
	v_xor_b32_e32 v157, s100, v157
	v_or3_b32 v150, v154, v155, v156
	v_or_b32_e32 v150, v150, v157
	v_cmp_gt_i32_e32 vcc, 0, v150
	s_cbranch_vccz .Lrsx_ok1
	s_sleep 1
	s_add_i32 s101, s101, -1
	s_cmp_lg_u32 s101, 0
	s_cbranch_scc1 .Lrsx_poll1
.Lrsx_ok1:
	v_add_f32_e32 v150, v154, v155
	v_add_f32_e32 v156, v156, v157
	v_add_f32_e32 v32, v150, v156
	v_fmamk_f32 v32, v32, 0x3a800000, v239
	v_mul_f32_e32 v150, 0x4b800000, v32
	v_cmp_gt_f32_e32 vcc, s34, v32
	s_nop 1
	v_cndmask_b32_e32 v32, v32, v150, vcc
	v_rsq_f32_e32 v32, v32
	s_nop 0
	v_mul_f32_e32 v150, 0x45800000, v32
	v_cndmask_b32_e32 v32, v32, v150, vcc
	ds_write_b32 v174, v32 offset:4096

.LBB0_1663:
	s_or_b64 exec, exec, s[34:35]
	v_readlane_b32 s100, v254, 16
	s_lshl_b32 s100, s100, 31
	s_add_u32 s0, s18, s48
	s_addc_u32 s11, s19, s49
	s_add_u32 s10, s0, 0x5840000
	s_addc_u32 s11, s11, 0
	s_waitcnt lgkmcnt(0)
	s_barrier
	s_and_saveexec_b64 s[34:35], s[8:9]
	s_cbranch_execz .LBB0_1665
	ds_read_b128 v[46:49], v175
	v_lshl_add_u64 v[50:51], v[34:35], 2, s[10:11]
	s_ashr_i32 s43, s42, 31
	v_lshl_add_u64 v[50:51], s[42:43], 2, v[50:51]
	s_waitcnt lgkmcnt(0)
	v_mov_b32_e32 v52, v47
	v_mov_b32_e32 v53, v48
	v_mov_b32_e32 v47, v49
	v_pk_add_f32 v[46:47], v[52:53], v[46:47]
	s_nop 0
	v_pk_add_f32 v[46:47], v[46:47], v[46:47] op_sel:[0,1] op_sel_hi:[1,0]
	v_or_b32_e32 v46, s100, v46
	global_store_dword v[50:51], v46, off sc1
.LBB0_1665:
	s_or_b64 exec, exec, s[34:35]
	s_and_saveexec_b64 s[12:13], s[8:9]
	s_cbranch_execz .LBB0_1681
	v_lshl_add_u64 v[50:51], v[34:35], 2, s[10:11]
	s_mov_b32 s0, 0x800000
	s_movk_i32 s101, 0x7fff
.Lrsx_poll2:
	global_load_dwordx4 v[46:49], v[50:51], off sc1
	s_waitcnt vmcnt(0)
	v_xor_b32_e32 v46, s100, v46
	v_xor_b32_e32 v47, s100, v47
	v_xor_b32_e32 v48, s100, v48
	v_xor_b32_e32 v49, s100, v49
	v_or3_b32 v34, v46, v47, v48
	v_or_b32_e32 v34, v34, v49
	v_cmp_gt_i32_e32 vcc, 0, v34
	s_cbranch_vccz .Lrsx_ok2
	s_sleep 1
	s_add_i32 s101, s101, -1
	s_cmp_lg_u32 s101, 0
	s_cbranch_scc1 .Lrsx_poll2
.Lrsx_ok2:
	v_add_f32_e32 v34, v46, v47
	v_add_f32_e32 v48, v48, v49
	v_add_f32_e32 v32, v34, v48
	v_fmamk_f32 v32, v32, 0x3a800000, v239
	v_mul_f32_e32 v34, 0x4b800000, v32
	v_cmp_gt_f32_e32 vcc, s0, v32
	s_nop 1
	v_cndmask_b32_e32 v32, v32, v34, vcc
	v_rsq_f32_e32 v32, v32
	s_nop 0
	v_mul_f32_e32 v34, 0x45800000, v32
	v_cndmask_b32_e32 v32, v32, v34, vcc
	ds_write_b32 v174, v32 offset:4096

.LBB0_1754:
	s_or_b64 exec, exec, s[10:11]
	v_readlane_b32 s100, v254, 16
	s_lshl_b32 s100, s100, 31
	s_ashr_i32 s47, s46, 31
	s_lshl_b64 s[42:43], s[46:47], 12
	s_add_u32 s5, s18, s42
	s_addc_u32 s10, s19, s43
	s_add_u32 s34, s5, 0x5800000
	v_lshlrev_b32_e32 v154, 2, v32
	s_addc_u32 s35, s10, 0
	v_ashrrev_i32_e32 v155, 31, v154
	v_lshl_add_u32 v173, v32, 4, 0
	s_waitcnt vmcnt(0) lgkmcnt(0)
	s_barrier
	s_and_saveexec_b64 s[10:11], s[6:7]
	s_cbranch_execz .LBB0_1756
	ds_read_b128 v[158:161], v173
	v_lshl_add_u64 v[162:163], v[154:155], 2, s[34:35]
	s_ashr_i32 s13, s12, 31
	v_lshl_add_u64 v[162:163], s[12:13], 2, v[162:163]
	s_waitcnt lgkmcnt(0)
	v_mov_b32_e32 v164, v159
	v_mov_b32_e32 v165, v160
	v_mov_b32_e32 v159, v161
	v_pk_add_f32 v[158:159], v[164:165], v[158:159]
	s_nop 0
	v_pk_add_f32 v[158:159], v[158:159], v[158:159] op_sel:[0,1] op_sel_hi:[1,0]
	v_or_b32_e32 v158, s100, v158
	global_store_dword v[162:163], v158, off sc1
.LBB0_1756:
	s_or_b64 exec, exec, s[10:11]
	s_add_u32 s5, s18, 0x8000
	s_addc_u32 s31, s19, 0
	s_lshl_b32 s16, s46, 4
	v_cmp_eq_u32_e64 s[10:11], 0, v32
	v_add_u32_e32 v172, 0, v154
	s_and_saveexec_b64 s[48:49], s[6:7]
	s_cbranch_execz .LBB0_1772
	v_lshl_add_u64 v[162:163], v[154:155], 2, s[34:35]
	s_mov_b32 s13, 0x800000
	s_movk_i32 s101, 0x7fff
.Lrsx_poll3:
	global_load_dwordx4 v[158:161], v[162:163], off sc1
	s_waitcnt vmcnt(0)
	v_xor_b32_e32 v158, s100, v158
	v_xor_b32_e32 v159, s100, v159
	v_xor_b32_e32 v160, s100, v160
	v_xor_b32_e32 v161, s100, v161
	v_or3_b32 v156, v158, v159, v160
	v_or_b32_e32 v156, v156, v161
	v_cmp_gt_i32_e32 vcc, 0, v156
	s_cbranch_vccz .Lrsx_ok3
	s_sleep 1
	s_add_i32 s101, s101, -1
	s_cmp_lg_u32 s101, 0
	s_cbranch_scc1 .Lrsx_poll3
.Lrsx_ok3:
	v_add_f32_e32 v156, v158, v159
	v_add_f32_e32 v160, v160, v161
	v_add_f32_e32 v32, v156, v160
	v_fmamk_f32 v32, v32, 0x3a800000, v239
	v_mul_f32_e32 v156, 0x4b800000, v32
	v_cmp_gt_f32_e32 vcc, s13, v32
	s_nop 1
	v_cndmask_b32_e32 v32, v32, v156, vcc
	v_rsq_f32_e32 v32, v32
	s_nop 0
	v_mul_f32_e32 v156, 0x45800000, v32
	v_cndmask_b32_e32 v32, v32, v156, vcc
	ds_write_b32 v172, v32 offset:4096

.LBB0_1774:
	s_or_b64 exec, exec, s[34:35]
	v_readlane_b32 s100, v254, 16
	s_lshl_b32 s100, s100, 31
	s_add_u32 s0, s18, s42
	s_addc_u32 s9, s19, s43
	s_add_u32 s8, s0, 0x5840000
	s_addc_u32 s9, s9, 0
	s_waitcnt lgkmcnt(0)
	s_barrier
	s_and_saveexec_b64 s[34:35], s[6:7]
	s_cbranch_execz .LBB0_1776
	ds_read_b128 v[24:27], v173
	v_lshl_add_u64 v[28:29], v[154:155], 2, s[8:9]
	s_ashr_i32 s13, s12, 31
	v_lshl_add_u64 v[28:29], s[12:13], 2, v[28:29]
	s_waitcnt lgkmcnt(0)
	v_mov_b32_e32 v30, v25
	v_mov_b32_e32 v31, v26
	v_mov_b32_e32 v25, v27
	v_pk_add_f32 v[24:25], v[30:31], v[24:25]
	s_nop 0
	v_pk_add_f32 v[24:25], v[24:25], v[24:25] op_sel:[0,1] op_sel_hi:[1,0]
	v_or_b32_e32 v24, s100, v24
	global_store_dword v[28:29], v24, off sc1
.LBB0_1776:
	s_or_b64 exec, exec, s[34:35]
	s_and_saveexec_b64 s[10:11], s[6:7]
	s_cbranch_execz .LBB0_1792
	v_lshl_add_u64 v[28:29], v[154:155], 2, s[8:9]
	s_mov_b32 s0, 0x800000
	s_movk_i32 s101, 0x7fff
.Lrsx_poll4:
	global_load_dwordx4 v[24:27], v[28:29], off sc1
	s_waitcnt vmcnt(0)
	v_xor_b32_e32 v24, s100, v24
	v_xor_b32_e32 v25, s100, v25
	v_xor_b32_e32 v26, s100, v26
	v_xor_b32_e32 v27, s100, v27
	v_or3_b32 v30, v24, v25, v26
	v_or_b32_e32 v30, v30, v27
	v_cmp_gt_i32_e32 vcc, 0, v30
	s_cbranch_vccz .Lrsx_ok4
	s_sleep 1
	s_add_i32 s101, s101, -1
	s_cmp_lg_u32 s101, 0
	s_cbranch_scc1 .Lrsx_poll4
.Lrsx_ok4:
	v_add_f32_e32 v30, v24, v25
	v_add_f32_e32 v26, v26, v27
	v_add_f32_e32 v24, v30, v26
	v_fmamk_f32 v24, v24, 0x3a800000, v239
	v_mul_f32_e32 v25, 0x4b800000, v24
	v_cmp_gt_f32_e32 vcc, s0, v24
	s_nop 1
	v_cndmask_b32_e32 v24, v24, v25, vcc
	v_rsq_f32_e32 v24, v24
	s_nop 0
	v_mul_f32_e32 v25, 0x45800000, v24
	v_cndmask_b32_e32 v24, v24, v25, vcc
	ds_write_b32 v172, v24 offset:4096
